# State scan: ring-offset scalar math carried from the loop tail instead of recomputed at the loop top; record-builder prefetch block keeps the workspace pointer in registers instead of reloading it eac
# baseline (speedup 1.0000x reference)
.LBB0_317:
	v_writelane_b32 v249, s0, 38
	s_and_b64 vcc, exec, s[2:3]
	s_nop 0
	v_writelane_b32 v249, s1, 39
	s_cbranch_vccz .LBB0_905
	s_cmp_eq_u32 s80, 4
	s_cselect_b64 s[0:1], -1, 0
	s_cmp_lg_u32 s80, 4
	s_cselect_b64 s[2:3], -1, 0
	v_writelane_b32 v249, s2, 40
	s_cmp_lt_u32 s8, 9
	s_cselect_b64 s[72:73], -1, 0
	v_writelane_b32 v249, s3, 41
	v_writelane_b32 v249, s0, 42
	s_mov_b64 s[46:47], 0x1000
	s_nop 0
	v_writelane_b32 v249, s1, 43
	s_and_b64 s[0:1], s[0:1], s[72:73]
	s_andn2_b64 vcc, exec, s[0:1]
	s_cbranch_vccnz .LBB0_486
	s_cmpk_gt_i32 s64, 0x8ff
	s_cbranch_scc1 .LBB0_342
	v_readlane_b32 s0, v249, 36
	s_lshl_b32 s8, s64, 2
	s_lshl_b32 s9, s0, 2
	s_mov_b32 s22, s64
	v_readlane_b32 s1, v249, 37
	s_mov_b32 s100, s8
	v_mbcnt_lo_u32_b32 v166, -1, 0
	v_mbcnt_hi_u32_b32 v166, -1, v166
	v_add_u32_e32 v167, s61, v166
	v_lshrrev_b32_e32 v168, 7, v167
	v_add_u32_e32 v168, s100, v168
	s_load_dwordx2 s[100:101], s[58:59], 0x158
	v_lshlrev_b32_e32 v169, 4, v168
	v_and_b32_e32 v169, 0x7f0, v169
	v_ashrrev_i32_e32 v170, 10, v168
	v_lshl_or_b32 v170, v170, 11, v169
	v_lshrrev_b32_e32 v171, 7, v168
	v_add_u32_e32 v172, 0xffffe000, v168
	v_and_b32_e32 v172, -8, v172
	v_add_u32_e32 v172, 0x4000, v172
	v_cmp_lt_i32_e32 vcc, 0x1fff, v168
	s_nop 1
	v_cndmask_b32_e32 v170, v170, v172, vcc
	v_cndmask_b32_e64 v169, v169, 0, vcc
	v_cndmask_b32_e32 v171, v171, v168, vcc
	v_mov_b32_e32 v173, 16
	v_cndmask_b32_e64 v173, v173, 8, vcc
	v_bfe_u32 v174, v167, 6, 1
	v_bfe_u32 v175, v166, 3, 3
	v_lshl_or_b32 v174, v174, 3, v175
	v_cmp_gt_u32_e32 vcc, v173, v174
	s_nop 1
	v_cndmask_b32_e32 v174, 0, v174, vcc
	v_lshlrev_b32_e32 v171, 6, v171
	v_and_b32_e32 v171, 0x1c0, v171
	v_lshlrev_b32_e32 v175, 3, v167
	v_and_b32_e32 v175, 56, v175
	v_or_b32_e32 v171, v171, v175
	v_add_u32_e32 v170, v170, v174
	v_or_b32_e32 v169, v169, v174
	v_lshlrev_b32_e32 v176, 1, v171
	v_mov_b32_e32 v177, 0
	v_mov_b32_e32 v178, 0xc00
	s_waitcnt lgkmcnt(0)
	v_mov_b64_e32 v[186:187], s[100:101]
	v_mov_b64_e32 v[180:181], s[100:101]
	v_mov_b64_e32 v[182:183], s[100:101]
	v_mad_i64_i32 v[180:181], vcc, v170, s83, v[180:181]
	v_mad_i64_i32 v[182:183], vcc, v170, v178, v[182:183]
	v_lshl_add_u64 v[180:181], v[180:181], 0, v[176:177]
	v_lshl_add_u64 v[182:183], v[182:183], 0, v[176:177]
	v_add_co_u32_e32 v180, vcc, 0x12f01000, v180
	s_nop 1
	v_addc_co_u32_e32 v181, vcc, 0, v181, vcc
	v_add_co_u32_e32 v182, vcc, 0x25600000, v182
	s_nop 1
	v_addc_co_u32_e32 v183, vcc, 0, v183, vcc
	v_cmp_eq_u32_e32 vcc, 0, v169
	s_nop 1
	v_cndmask_b32_e64 v185, -1, 0, vcc
	v_cndmask_b32_e64 v184, v205, 0, vcc
	v_lshl_add_u64 v[184:185], v[180:181], 0, v[184:185]
	global_load_dwordx4 v[128:131], v[182:183], off
	global_load_dwordx4 v[132:135], v[184:185], off
	global_load_dwordx4 v[136:139], v[184:185], off offset:1024
	global_load_dwordx4 v[140:143], v[180:181], off offset:1024
	global_load_dwordx4 v[144:147], v[180:181], off offset:2048
	global_load_dwordx4 v[148:151], v[180:181], off
	global_load_dwordx4 v[152:155], v[184:185], off offset:2048
	global_load_dwordx4 v[158:161], v[182:183], off offset:1024
	global_load_dwordx4 v[162:165], v[182:183], off offset:2048
	s_branch .LBB0_322

.LBB0_332:
	s_or_b64 exec, exec, s[12:13]
	s_add_i32 s100, s8, s9
	s_cmpk_ge_i32 s100, 0x2400
	s_cbranch_scc1 .Lr1pf_skip
	v_mbcnt_lo_u32_b32 v166, -1, 0
	v_mbcnt_hi_u32_b32 v166, -1, v166
	v_add_u32_e32 v167, s61, v166
	v_lshrrev_b32_e32 v168, 7, v167
	v_add_u32_e32 v168, s100, v168
	v_lshlrev_b32_e32 v169, 4, v168
	v_and_b32_e32 v169, 0x7f0, v169
	v_ashrrev_i32_e32 v170, 10, v168
	v_lshl_or_b32 v170, v170, 11, v169
	v_lshrrev_b32_e32 v171, 7, v168
	v_add_u32_e32 v172, 0xffffe000, v168
	v_and_b32_e32 v172, -8, v172
	v_add_u32_e32 v172, 0x4000, v172
	v_cmp_lt_i32_e32 vcc, 0x1fff, v168
	s_nop 1
	v_cndmask_b32_e32 v170, v170, v172, vcc
	v_cndmask_b32_e64 v169, v169, 0, vcc
	v_cndmask_b32_e32 v171, v171, v168, vcc
	v_mov_b32_e32 v173, 16
	v_cndmask_b32_e64 v173, v173, 8, vcc
	v_bfe_u32 v174, v167, 6, 1
	v_bfe_u32 v175, v166, 3, 3
	v_lshl_or_b32 v174, v174, 3, v175
	v_cmp_gt_u32_e32 vcc, v173, v174
	s_nop 1
	v_cndmask_b32_e32 v174, 0, v174, vcc
	v_lshlrev_b32_e32 v171, 6, v171
	v_and_b32_e32 v171, 0x1c0, v171
	v_lshlrev_b32_e32 v175, 3, v167
	v_and_b32_e32 v175, 56, v175
	v_or_b32_e32 v171, v171, v175
	v_add_u32_e32 v170, v170, v174
	v_or_b32_e32 v169, v169, v174
	v_lshlrev_b32_e32 v176, 1, v171
	v_mov_b32_e32 v177, 0
	v_mov_b32_e32 v178, 0xc00
	v_mov_b64_e32 v[180:181], v[186:187]
	v_mov_b64_e32 v[182:183], v[186:187]
	v_mad_i64_i32 v[180:181], vcc, v170, s83, v[180:181]
	v_mad_i64_i32 v[182:183], vcc, v170, v178, v[182:183]
	v_lshl_add_u64 v[180:181], v[180:181], 0, v[176:177]
	v_lshl_add_u64 v[182:183], v[182:183], 0, v[176:177]
	v_add_co_u32_e32 v180, vcc, 0x12f01000, v180
	s_nop 1
	v_addc_co_u32_e32 v181, vcc, 0, v181, vcc
	v_add_co_u32_e32 v182, vcc, 0x25600000, v182
	s_nop 1
	v_addc_co_u32_e32 v183, vcc, 0, v183, vcc
	v_cmp_eq_u32_e32 vcc, 0, v169
	s_nop 1
	v_cndmask_b32_e64 v185, -1, 0, vcc
	v_cndmask_b32_e64 v184, v205, 0, vcc
	v_lshl_add_u64 v[184:185], v[180:181], 0, v[184:185]
	global_load_dwordx4 v[128:131], v[182:183], off
	global_load_dwordx4 v[132:135], v[184:185], off
	global_load_dwordx4 v[136:139], v[184:185], off offset:1024
	global_load_dwordx4 v[140:143], v[180:181], off offset:1024
	global_load_dwordx4 v[144:147], v[180:181], off offset:2048
	global_load_dwordx4 v[148:151], v[180:181], off
	global_load_dwordx4 v[152:155], v[184:185], off offset:2048
	global_load_dwordx4 v[158:161], v[182:183], off offset:1024
	global_load_dwordx4 v[162:165], v[182:183], off offset:2048

.LBB0_430:
	v_lshrrev_b32_e32 v33, 5, v148
	v_mov_b32_e32 v15, 0
	v_and_b32_e32 v149, 31, v32
	s_andn2_b64 vcc, exec, s[2:3]
	v_lshlrev_b32_e32 v144, 4, v33
	v_mov_b32_e32 v14, v15
	v_mov_b32_e32 v13, v15
	v_mov_b32_e32 v12, v15
	v_mov_b32_e32 v11, v15
	v_mov_b32_e32 v10, v15
	v_mov_b32_e32 v9, v15
	v_mov_b32_e32 v8, v15
	v_mov_b32_e32 v7, v15
	v_mov_b32_e32 v6, v15
	v_mov_b32_e32 v5, v15
	v_mov_b32_e32 v4, v15
	v_mov_b32_e32 v3, v15
	v_mov_b32_e32 v2, v15
	v_mov_b32_e32 v1, v15
	v_mov_b32_e32 v0, v15
	v_mov_b32_e32 v31, v15
	v_mov_b32_e32 v30, v15
	v_mov_b32_e32 v29, v15
	v_mov_b32_e32 v28, v15
	v_mov_b32_e32 v27, v15
	v_mov_b32_e32 v26, v15
	v_mov_b32_e32 v25, v15
	v_mov_b32_e32 v24, v15
	v_mov_b32_e32 v23, v15
	v_mov_b32_e32 v22, v15
	v_mov_b32_e32 v21, v15
	v_mov_b32_e32 v20, v15
	v_mov_b32_e32 v19, v15
	v_mov_b32_e32 v18, v15
	v_mov_b32_e32 v17, v15
	v_mov_b32_e32 v16, v15
	s_cbranch_vccnz .LBB0_436
	s_setprio 3
	v_lshl_or_b32 v0, s9, 5, v149
	v_and_b32_e32 v1, 15, v32
	v_mul_lo_u32 v150, v0, 48
	v_add_u32_e32 v151, 0, v144
	v_mad_u32_u24 v2, v1, s42, 0
	v_lshlrev_b32_e32 v153, 3, v33
	v_add_u32_e32 v0, v151, v150
	v_mul_u32_u24_e32 v152, 0x88, v1
	v_add_u32_e32 v3, v2, v153
	v_mul_u32_u24_e32 v154, 48, v1
	v_mul_i32_i24_e32 v1, 0xffffffa8, v1
	ds_read2_b64 v[48:51], v3 offset1:2
	ds_read2_b64 v[52:55], v3 offset0:4 offset1:6
	ds_read2_b64 v[56:59], v3 offset0:8 offset1:10
	ds_read2_b64 v[60:63], v3 offset0:12 offset1:14
	v_add3_u32 v1, v2, v1, v144
	ds_read_b128 v[64:67], v0 offset:14720
	ds_read_b128 v[68:71], v1 offset:2176
	v_add_u32_e32 v0, 0, v153
	v_mad_u32_u24 v1, v149, s42, v0
	v_add_u32_e32 v2, 0x800, v1
	v_mul_u32_u24_e32 v156, 48, v149
	v_add_u32_e32 v1, 0x1800, v1
	ds_read2_b64 v[72:75], v2 offset0:112 offset1:114
	ds_read2_b64 v[76:79], v2 offset0:116 offset1:118
	ds_read2_b64 v[80:83], v2 offset0:120 offset1:122
	ds_read2_b64 v[84:87], v2 offset0:124 offset1:126
	v_add3_u32 v0, v0, v153, v156
	ds_read2_b64 v[88:91], v1 offset0:144 offset1:146
	ds_read2_b64 v[92:95], v1 offset0:148 offset1:150
	ds_read2_b64 v[96:99], v1 offset0:152 offset1:154
	ds_read2_b64 v[100:103], v1 offset0:156 offset1:158
	ds_read_b128 v[104:107], v0 offset:11648
	ds_read_b128 v[108:111], v0 offset:13184
	s_lshl_b32 s0, s9, 7
	s_add_i32 s0, s0, 0
	v_lshlrev_b32_e32 v0, 10, v33
	s_add_i32 s1, s0, 0x1f800
	v_lshlrev_b32_e32 v1, 2, v149
	s_add_i32 s0, s0, 0x20800
	v_mov_b32_e32 v16, 0
	v_mul_u32_u24_e32 v155, 0x88, v149
	v_add3_u32 v158, s1, v0, v1
	v_add3_u32 v159, s0, v0, v1
	s_mov_b32 s0, 0
	v_mov_b32_e32 v17, v16
	v_mov_b32_e32 v18, v16
	v_mov_b32_e32 v19, v16
	v_mov_b32_e32 v20, v16
	v_mov_b32_e32 v21, v16
	v_mov_b32_e32 v22, v16
	v_mov_b32_e32 v23, v16
	v_mov_b32_e32 v24, v16
	v_mov_b32_e32 v25, v16
	v_mov_b32_e32 v26, v16
	v_mov_b32_e32 v27, v16
	v_mov_b32_e32 v28, v16
	v_mov_b32_e32 v29, v16
	v_mov_b32_e32 v30, v16
	v_mov_b32_e32 v31, v16
	v_mov_b32_e32 v0, v16
	v_mov_b32_e32 v1, v16
	v_mov_b32_e32 v2, v16
	v_mov_b32_e32 v3, v16
	v_mov_b32_e32 v4, v16
	v_mov_b32_e32 v5, v16
	v_mov_b32_e32 v6, v16
	v_mov_b32_e32 v7, v16
	v_mov_b32_e32 v8, v16
	v_mov_b32_e32 v9, v16
	v_mov_b32_e32 v10, v16
	v_mov_b32_e32 v11, v16
	v_mov_b32_e32 v12, v16
	v_mov_b32_e32 v13, v16
	v_mov_b32_e32 v14, v16
	v_mov_b32_e32 v15, v16
	s_mov_b32 s1, 0
	s_branch .LBB0_433

.LBB0_433:
	v_add_u32_e32 v136, s1, v151
	ds_read_b128 v[228:231], v136 offset:17792
	ds_read_b128 v[232:235], v136 offset:17824
	ds_read_b128 v[236:239], v136 offset:17856
	ds_read_b128 v[240:243], v136 offset:17888
	ds_read_b128 v[128:131], v136 offset:17920
	ds_read_b128 v[132:135], v136 offset:17952
	ds_read_b128 v[220:223], v136 offset:17984
	ds_read_b128 v[224:227], v136 offset:18016
	v_cvt_pk_bf16_f32 v112, v16, v17
	v_cvt_pk_bf16_f32 v113, v18, v19
	v_cvt_pk_bf16_f32 v114, v20, v21
	v_cvt_pk_bf16_f32 v115, v22, v23
	v_cvt_pk_bf16_f32 v116, v24, v25
	v_cvt_pk_bf16_f32 v117, v26, v27
	v_cvt_pk_bf16_f32 v118, v28, v29
	v_cvt_pk_bf16_f32 v119, v30, v31
	s_nop 1
	v_mfma_f32_32x32x16_bf16 v[32:47], v[48:51], v[112:115], 0
	v_mfma_f32_32x32x16_bf16 v[32:47], v[52:55], v[116:119], v[32:47]
	v_cvt_pk_bf16_f32 v120, v0, v1
	v_cvt_pk_bf16_f32 v121, v2, v3
	v_cvt_pk_bf16_f32 v122, v4, v5
	v_cvt_pk_bf16_f32 v123, v6, v7
	v_cvt_pk_bf16_f32 v124, v8, v9
	v_cvt_pk_bf16_f32 v125, v10, v11
	v_cvt_pk_bf16_f32 v126, v12, v13
	v_cvt_pk_bf16_f32 v127, v14, v15
	s_waitcnt lgkmcnt(0)
	v_pk_mul_f32 v[16:17], v[16:17], v[228:229]
	v_pk_mul_f32 v[18:19], v[18:19], v[230:231]
	v_pk_mul_f32 v[20:21], v[20:21], v[232:233]
	v_pk_mul_f32 v[22:23], v[22:23], v[234:235]
	v_pk_mul_f32 v[24:25], v[24:25], v[236:237]
	v_pk_mul_f32 v[26:27], v[26:27], v[238:239]
	v_pk_mul_f32 v[28:29], v[28:29], v[240:241]
	v_pk_mul_f32 v[30:31], v[30:31], v[242:243]
	v_mul_f32_e64 v0, v0, v128
	v_mul_f32_e64 v1, v1, v129
	v_mul_f32_e64 v2, v2, v130
	v_mul_f32_e64 v3, v3, v131
	v_mul_f32_e64 v4, v4, v132
	v_mul_f32_e64 v5, v5, v133
	v_pk_mul_f32 v[6:7], v[6:7], v[134:135]
	s_or_b32 s1, s0, 1
	v_mfma_f32_32x32x16_bf16 v[16:31], v[72:75], v[112:115], v[16:31]
	s_and_b32 s2, s1, 0xff
	v_mul_f32_e64 v8, v8, v220
	v_mul_f32_e64 v9, v9, v221
	v_mul_f32_e64 v10, v10, v222
	v_mul_f32_e64 v11, v11, v223
	v_pk_mul_f32 v[12:13], v[12:13], v[224:225]
	v_pk_mul_f32 v[14:15], v[14:15], v[226:227]
	s_mul_i32 s2, s2, 37
	s_lshr_b32 s2, s2, 8
	s_sub_i32 s3, s1, s2
	s_bfe_u32 s3, s3, 0x70001
	s_add_i32 s3, s3, s2
	s_lshr_b32 s2, s3, 2
	s_mul_i32 s2, s2, 7
	s_sub_i32 s1, s1, s2
	s_and_b32 s1, s1, 0xff
	v_mfma_f32_32x32x16_bf16 v[0:15], v[88:91], v[112:115], v[0:15]
	s_mulk_i32 s1, 0x4800
	s_add_i32 s1, s1, 0
	v_add_u32_e32 v192, s1, v144
	v_add_u32_e32 v180, v192, v156
	s_cmpk_gt_u32 s0, 0x7d
	s_cselect_b64 s[2:3], -1, 0
	v_mfma_f32_32x32x16_bf16 v[16:31], v[76:79], v[116:119], v[16:31]
	s_and_b64 vcc, exec, s[2:3]
	v_mfma_f32_32x32x16_bf16 v[32:47], v[56:59], v[120:123], v[32:47]
	v_mfma_f32_32x32x16_bf16 v[0:15], v[92:95], v[116:119], v[0:15]
	v_mfma_f32_32x32x16_bf16 v[16:31], v[80:83], v[120:123], v[16:31]
	v_mfma_f32_32x32x16_bf16 v[32:47], v[60:63], v[124:127], v[32:47]
	v_mfma_f32_32x32x16_bf16 v[0:15], v[96:99], v[120:123], v[0:15]
	v_mfma_f32_32x32x16_bf16 v[16:31], v[84:87], v[124:127], v[16:31]
	v_mfma_f32_32x32x16_bf16 v[32:47], v[68:71], v[64:67], v[32:47]
	v_mfma_f32_32x32x16_bf16 v[0:15], v[100:103], v[124:127], v[0:15]
	s_nop 10
	v_add_u32_e32 v45, s1, v153
	v_add_u32_e32 v46, v45, v152
	v_add_u32_e32 v160, v45, v155
	v_add_u32_e32 v44, v192, v150
	ds_read2_b64 v[40:43], v46 offset1:2
	ds_read2_b64 v[116:119], v46 offset0:4 offset1:6
	ds_read2_b64 v[120:123], v46 offset0:8 offset1:10
	ds_read2_b64 v[124:127], v46 offset0:12 offset1:14
	v_add_u32_e32 v46, v192, v154
	v_add_u32_e32 v132, 0x800, v160
	v_mfma_f32_32x32x16_bf16 v[16:31], v[104:107], v[64:67], v[16:31]
	v_add_u32_e32 v172, 0x1800, v160
	ds_read_b128 v[112:115], v44 offset:14720
	ds_read_b128 v[128:131], v46 offset:2176
	ds_read2_b64 v[44:47], v132 offset0:112 offset1:114
	ds_read2_b64 v[140:143], v132 offset0:116 offset1:118
	ds_read2_b64 v[136:139], v132 offset0:120 offset1:122
	ds_read2_b64 v[132:135], v132 offset0:124 offset1:126
	ds_read2_b64 v[160:163], v172 offset0:144 offset1:146
	ds_read2_b64 v[164:167], v172 offset0:148 offset1:150
	ds_read2_b64 v[168:171], v172 offset0:152 offset1:154
	ds_read2_b64 v[172:175], v172 offset0:156 offset1:158
	ds_read_b128 v[176:179], v180 offset:11648
	ds_read_b128 v[180:183], v180 offset:13184
	ds_read_b128 v[220:223], v192 offset:17888
	ds_read_b128 v[224:227], v192 offset:17856
	ds_read_b128 v[228:231], v192 offset:17824
	ds_read_b128 v[232:235], v192 offset:17792
	ds_read_b128 v[236:239], v192 offset:18016
	ds_read_b128 v[240:243], v192 offset:17984
	ds_read_b128 v[244:247], v192 offset:17952
	ds_write2st64_b32 v158, v32, v33 offset1:1
	ds_write2st64_b32 v158, v34, v35 offset0:2 offset1:3
	ds_write2st64_b32 v158, v36, v37 offset0:8 offset1:9
	ds_write2st64_b32 v158, v38, v39 offset0:10 offset1:11
	s_waitcnt lgkmcnt(0)
	s_barrier
	ds_read_b128 v[36:39], v192 offset:17920
	v_cvt_pk_bf16_f32 v32, v16, v17
	v_mfma_f32_32x32x16_bf16 v[0:15], v[108:111], v[64:67], v[0:15]
	v_cvt_pk_bf16_f32 v33, v18, v19
	v_cvt_pk_bf16_f32 v34, v20, v21
	v_cvt_pk_bf16_f32 v35, v22, v23
	v_cvt_pk_bf16_f32 v184, v24, v25
	v_cvt_pk_bf16_f32 v185, v26, v27
	v_cvt_pk_bf16_f32 v186, v28, v29
	v_cvt_pk_bf16_f32 v187, v30, v31
	v_cvt_pk_bf16_f32 v188, v0, v1
	v_cvt_pk_bf16_f32 v189, v2, v3
	v_cvt_pk_bf16_f32 v190, v4, v5
	v_cvt_pk_bf16_f32 v191, v6, v7
	v_cvt_pk_bf16_f32 v216, v8, v9
	v_cvt_pk_bf16_f32 v217, v10, v11
	v_cvt_pk_bf16_f32 v218, v12, v13
	v_cvt_pk_bf16_f32 v219, v14, v15
	v_pk_mul_f32 v[28:29], v[28:29], v[220:221]
	v_pk_mul_f32 v[30:31], v[30:31], v[222:223]
	v_pk_mul_f32 v[24:25], v[24:25], v[224:225]
	v_pk_mul_f32 v[26:27], v[26:27], v[226:227]
	v_pk_mul_f32 v[20:21], v[20:21], v[228:229]
	v_pk_mul_f32 v[22:23], v[22:23], v[230:231]
	v_pk_mul_f32 v[18:19], v[18:19], v[234:235]
	v_pk_mul_f32 v[16:17], v[16:17], v[232:233]
	v_pk_mul_f32 v[12:13], v[12:13], v[236:237]
	v_pk_mul_f32 v[14:15], v[14:15], v[238:239]
	v_mfma_f32_32x32x16_bf16 v[16:31], v[44:47], v[32:35], v[16:31]
	v_mul_f32_e64 v8, v8, v240
	v_mul_f32_e64 v9, v9, v241
	v_mul_f32_e64 v10, v10, v242
	v_mul_f32_e64 v11, v11, v243
	v_pk_mul_f32 v[4:5], v[4:5], v[244:245]
	v_pk_mul_f32 v[6:7], v[6:7], v[246:247]
	v_mfma_f32_32x32x16_bf16 v[16:31], v[140:143], v[184:187], v[16:31]
	s_waitcnt lgkmcnt(0)
	v_mul_f32_e64 v2, v2, v38
	v_mul_f32_e64 v3, v3, v39
	v_mul_f32_e64 v0, v0, v36
	v_mul_f32_e64 v1, v1, v37
	s_nop 1
	v_mfma_f32_32x32x16_bf16 v[0:15], v[160:163], v[32:35], v[0:15]
	v_mfma_f32_32x32x16_bf16 v[32:47], v[40:43], v[32:35], 0
	v_mfma_f32_32x32x16_bf16 v[32:47], v[116:119], v[184:187], v[32:47]
	v_mfma_f32_32x32x16_bf16 v[0:15], v[164:167], v[184:187], v[0:15]
	v_mfma_f32_32x32x16_bf16 v[32:47], v[120:123], v[188:191], v[32:47]
	v_mfma_f32_32x32x16_bf16 v[16:31], v[136:139], v[188:191], v[16:31]
	v_mfma_f32_32x32x16_bf16 v[0:15], v[168:171], v[188:191], v[0:15]
	v_mfma_f32_32x32x16_bf16 v[32:47], v[124:127], v[216:219], v[32:47]
	v_mfma_f32_32x32x16_bf16 v[16:31], v[132:135], v[216:219], v[16:31]
	v_mfma_f32_32x32x16_bf16 v[0:15], v[172:175], v[216:219], v[0:15]
	v_mfma_f32_32x32x16_bf16 v[32:47], v[128:131], v[112:115], v[32:47]
	v_mfma_f32_32x32x16_bf16 v[16:31], v[176:179], v[112:115], v[16:31]
	v_mfma_f32_32x32x16_bf16 v[0:15], v[180:183], v[112:115], v[0:15]
	s_cbranch_vccnz .LBB0_432
	s_add_i32 s1, s0, 2
	s_and_b32 s4, s1, 0xff
	s_mul_i32 s4, s4, 37
	s_lshr_b32 s5, s4, 8
	s_sub_i32 s5, s1, s5
	s_bfe_u32 s5, s5, 0x70001
	s_bfe_u32 s4, s4, 0x80008
	s_add_i32 s5, s5, s4
	s_bfe_u32 s4, s5, 0x60002
	s_mul_i32 s4, s4, 7
	s_sub_i32 s1, s1, s4
	s_and_b32 s1, s1, 0xff
	s_mulk_i32 s1, 0x4800
	s_add_i32 s1, s1, 0
	v_add_u32_e32 v40, s1, v144
	v_add_u32_e32 v42, s1, v153
	v_add_u32_e32 v41, v40, v150
	v_add_u32_e32 v43, v42, v152
	ds_read2_b64 v[48:51], v43 offset1:2
	ds_read2_b64 v[52:55], v43 offset0:4 offset1:6
	ds_read2_b64 v[56:59], v43 offset0:8 offset1:10
	ds_read2_b64 v[60:63], v43 offset0:12 offset1:14
	v_add_u32_e32 v43, v40, v154
	ds_read_b128 v[64:67], v41 offset:14720
	ds_read_b128 v[68:71], v43 offset:2176
	v_add_u32_e32 v41, v42, v155
	v_add_u32_e32 v42, 0x800, v41
	v_add_u32_e32 v41, 0x1800, v41
	ds_read2_b64 v[72:75], v42 offset0:112 offset1:114
	ds_read2_b64 v[76:79], v42 offset0:116 offset1:118
	ds_read2_b64 v[80:83], v42 offset0:120 offset1:122
	ds_read2_b64 v[84:87], v42 offset0:124 offset1:126
	v_add_u32_e32 v40, v40, v156
	ds_read2_b64 v[88:91], v41 offset0:144 offset1:146
	ds_read2_b64 v[92:95], v41 offset0:148 offset1:150
	ds_read2_b64 v[96:99], v41 offset0:152 offset1:154
	ds_read2_b64 v[100:103], v41 offset0:156 offset1:158
	ds_read_b128 v[104:107], v40 offset:11648
	ds_read_b128 v[108:111], v40 offset:13184
	s_branch .LBB0_432
